# gswap:11 on top of seldesc: NSA head group of a workgroup flips for units k>=8 (WGs c and c^4 trade half their units) to balance the two head groups
# speedup vs baseline: 1.0078x; 1.0078x over previous
.LBB0_1007:
	s_mov_b32 s90, s20
	s_lshl_b32 s0, s23, 13
	s_lshl_b32 s1, s20, 4
	s_and_b32 s40, s22, 3
	s_bfe_u32 s29, s22, 0x10002
	s_bfe_u32 s98, s22, 0x1000b
	s_xor_b32 s29, s29, s98
	s_lshl_b32 s74, s75, 4
	s_and_b32 s0, s0, 0x6000
	s_ashr_i32 s20, s1, 31
	s_add_u32 s0, s1, s0
	s_addc_u32 s1, s20, 0
	v_or_b32_e32 v0, s0, v130
	s_lshl_b32 s0, s23, 1
	v_mov_b32_e32 v1, s1
	s_and_b32 s0, s0, 8
	s_lshr_b32 s98, s23, 8
	s_and_b32 s98, s98, 8
	s_xor_b32 s0, s0, s98
	v_add_u32_e32 v4, s0, v131
	v_lshlrev_b64 v[0:1], 12, v[0:1]
	v_lshl_add_u64 v[0:1], s[36:37], 0, v[0:1]
	v_lshlrev_b32_e32 v2, 7, v4
	v_mov_b32_e32 v3, v123
	v_lshl_add_u64 v[2:3], v[0:1], 0, v[2:3]
	v_mov_b32_e32 v133, v123
	v_lshl_add_u64 v[2:3], v[2:3], 0, v[132:133]
	global_load_dwordx4 v[48:51], v[2:3], off
	global_load_dwordx4 v[52:55], v[2:3], off offset:64
	v_mul_u32_u24_e32 v2, 3, v4
	v_lshlrev_b32_e32 v2, 1, v2
	v_mov_b32_e32 v3, v123
	v_lshl_add_u64 v[0:1], v[0:1], 0, v[2:3]
	global_load_dword v133, v[0:1], off offset:3584
	global_load_ushort v185, v[0:1], off offset:3588
	v_lshl_add_u32 v184, s29, 3, v131
	v_add_u32_e32 v0, 1, v184
	v_cvt_f32_ubyte0_e32 v0, v0
	v_mul_f32_e32 v1, -0.5, v0
	v_cmp_gt_f32_e32 vcc, s64, v1
	s_lshl_b32 s0, s40, 1
	s_or_b32 s47, s0, s29
	v_cndmask_b32_e32 v1, 0, v177, vcc
	v_fmac_f32_e32 v1, -0.5, v0
	v_exp_f32_e32 v0, v1
	s_add_i32 s0, s75, -1
	s_ashr_i32 s0, s0, 6
	s_add_i32 s0, s0, 1
	v_cndmask_b32_e32 v1, 0, v178, vcc
	s_cmp_gt_i32 s75, 0
	v_ldexp_f32 v0, v0, v1
	s_cselect_b32 s20, s0, 0
	v_mov_b32_e32 v75, 0
	v_mul_f32_e32 v146, 0x3fb8aa3b, v0
	v_or_b32_e32 v144, s74, v130
	s_cmp_lt_i32 s20, 1
	v_add_u32_e32 v187, 0xa000, v152
	v_add_u32_e32 v186, 0xc800, v152
	v_mov_b32_e32 v74, 0
	v_mov_b32_e32 v73, 0
	v_mov_b32_e32 v72, 0
	v_mov_b32_e32 v79, 0
	v_mov_b32_e32 v78, 0
	v_mov_b32_e32 v77, 0
	v_mov_b32_e32 v76, 0
	v_mov_b32_e32 v71, 0
	v_mov_b32_e32 v70, 0
	v_mov_b32_e32 v69, 0
	v_mov_b32_e32 v68, 0
	v_mov_b32_e32 v67, 0
	v_mov_b32_e32 v66, 0
	v_mov_b32_e32 v65, 0
	v_mov_b32_e32 v64, 0
	v_mov_b32_e32 v80, 0
	v_mov_b32_e32 v81, 0
	s_cbranch_scc1 .LBB0_1027
	s_lshl_b32 s21, s47, 16
	s_add_u32 s0, s3, s21
	s_addc_u32 s1, s52, 0
	s_add_u32 s22, s53, s21
	s_addc_u32 s23, s54, 0
	s_add_i32 s21, s20, -1
	s_cmp_eq_u32 s20, 1
	s_cselect_b64 s[24:25], -1, 0
	s_and_b64 vcc, s[24:25], exec
	s_cselect_b32 s26, 0, 64
	s_lshl_b32 s24, s26, 7
	v_mov_b32_e32 v135, v123
	s_add_u32 s24, s0, s24
	v_lshl_add_u64 v[0:1], s[0:1], 0, v[134:135]
	v_mov_b32_e32 v137, v123
	s_addc_u32 s25, s1, 0
	s_lshl_b32 s26, s26, 1
	v_lshl_add_u64 v[44:45], v[0:1], 0, v[122:123]
	v_lshl_add_u64 v[0:1], s[22:23], 0, v[136:137]
	s_add_u32 s26, s22, s26
	v_lshl_add_u64 v[46:47], v[0:1], 0, v[122:123]
	s_addc_u32 s27, s23, 0
	v_lshl_add_u64 v[0:1], s[24:25], 0, v[134:135]
	v_mov_b32_e32 v8, v240
	v_mov_b32_e32 v9, v241
	v_mov_b32_e32 v10, v242
	v_mov_b32_e32 v11, v243
	v_mov_b32_e32 v12, v244
	v_mov_b32_e32 v13, v245
	v_mov_b32_e32 v14, v246
	v_mov_b32_e32 v15, v247
	v_lshl_add_u64 v[0:1], v[0:1], 0, v[122:123]
	v_lshl_add_u64 v[2:3], s[26:27], 0, v[136:137]
	v_lshl_add_u64 v[2:3], v[2:3], 0, v[122:123]
	v_mov_b32_e32 v16, v248
	v_mov_b32_e32 v17, v249
	v_mov_b32_e32 v18, v250
	v_mov_b32_e32 v19, v251
	v_mov_b32_e32 v20, v252
	v_mov_b32_e32 v21, v253
	v_mov_b32_e32 v22, v254
	v_mov_b32_e32 v23, v255
	s_min_u32 s26, s21, 2
	s_lshl_b32 s24, s26, 13
	s_add_u32 s24, s0, s24
	s_addc_u32 s25, s1, 0
	s_lshl_b32 s26, s26, 7
	s_add_u32 s26, s22, s26
	v_lshl_add_u64 v[0:1], s[24:25], 0, v[134:135]
	s_addc_u32 s27, s23, 0
	s_min_u32 s24, s21, 3
	s_lshl_b32 s25, s24, 13
	s_add_u32 s0, s0, s25
	v_lshl_add_u64 v[2:3], s[26:27], 0, v[136:137]
	s_addc_u32 s1, s1, 0
	s_lshl_b32 s24, s24, 7
	v_lshl_add_u64 v[0:1], v[0:1], 0, v[122:123]
	v_lshl_add_u64 v[2:3], v[2:3], 0, v[122:123]
	s_add_u32 s22, s22, s24
	global_load_dwordx4 v[4:7], v[0:1], off
	s_nop 0
	global_load_dwordx4 v[0:3], v[2:3], off
	v_lshl_add_u64 v[24:25], s[0:1], 0, v[134:135]
	s_addc_u32 s23, s23, 0
	v_lshl_add_u64 v[24:25], v[24:25], 0, v[122:123]
	v_lshl_add_u64 v[26:27], s[22:23], 0, v[136:137]
	v_lshl_add_u64 v[26:27], v[26:27], 0, v[122:123]
	v_mov_b32_e32 v75, 0
	s_mov_b32 s0, 0
	v_mov_b32_e32 v74, v75
	v_mov_b32_e32 v73, v75
	v_mov_b32_e32 v72, v75
	v_mov_b32_e32 v79, v75
	v_mov_b32_e32 v78, v75
	v_mov_b32_e32 v77, v75
	v_mov_b32_e32 v76, v75
	v_mov_b32_e32 v71, v75
	v_mov_b32_e32 v70, v75
	v_mov_b32_e32 v69, v75
	v_mov_b32_e32 v68, v75
	v_mov_b32_e32 v67, v75
	v_mov_b32_e32 v66, v75
	v_mov_b32_e32 v65, v75
	v_mov_b32_e32 v64, v75
	v_mov_b32_e32 v80, v75
	v_mov_b32_e32 v81, v75
	ds_write_b128 v151, v[8:11]
	ds_write2_b64 v187, v[12:13], v[14:15] offset1:2
	ds_write_b128 v151, v[16:19] offset:10240
	ds_write2_b64 v186, v[20:21], v[22:23] offset1:2
	global_load_dwordx4 v[12:15], v[24:25], off
	global_load_dwordx4 v[8:11], v[26:27], off
	s_waitcnt lgkmcnt(0)
	s_barrier
	s_cbranch_vccnz .LBB0_1021
	v_mov_b32_e32 v80, 0
	s_add_i32 s22, s75, -2
	v_mul_f32_e32 v82, 0x41800000, v146
	v_mul_f32_e32 v83, 0x42000000, v146
	v_mul_f32_e32 v84, 0x42400000, v146
	v_mul_f32_e32 v85, 0, v146
	s_waitcnt lgkmcnt(7)
	v_mul_f32_e32 v86, 0x43800000, v146
	v_mul_f32_e32 v87, 0x44000000, v146
	v_mul_f32_e32 v88, 0x44400000, v146
	v_add_u32_e32 v89, s74, v169
	s_mov_b32 s24, 5
	s_movk_i32 s23, 0xc0
	v_mov_b32_e32 v81, 0
	v_mov_b32_e32 v64, 0
	v_mov_b32_e32 v65, v80
	v_mov_b32_e32 v66, v80
	v_mov_b32_e32 v67, v80
	v_mov_b32_e32 v68, 0
	v_mov_b32_e32 v69, v80
	v_mov_b32_e32 v70, v80
	v_mov_b32_e32 v71, v80
	v_mov_b32_e32 v76, 0
	v_mov_b32_e32 v77, v80
	v_mov_b32_e32 v78, v80
	v_mov_b32_e32 v79, v80
	v_mov_b32_e32 v72, 0
	v_mov_b32_e32 v73, v80
	v_mov_b32_e32 v74, v80
	v_mov_b32_e32 v75, v80

.LBB0_1059:
	s_lshl_b32 s0, s80, 1
	s_add_u32 s0, s57, s0
	s_addc_u32 s1, s60, 0
	s_add_i32 s20, s74, 0xfffffe01
	s_andn2_b32 s20, s20, 63
	s_cmp_gt_i32 s75, 31
	s_cselect_b32 s20, s20, 0
	s_sub_i32 s21, s74, s20
	s_ashr_i32 s21, s21, 6
	s_min_i32 s22, s21, 0
	s_lshl_b32 s22, s22, 6
	s_add_i32 s22, s22, s20
	s_ashr_i32 s23, s22, 31
	s_lshl_b64 s[26:27], s[22:23], 12
	s_add_u32 s26, s24, s26
	s_addc_u32 s27, s25, s27
	s_lshl_b64 s[22:23], s[22:23], 1
	s_add_u32 s22, s0, s22
	s_addc_u32 s23, s1, s23
	v_mov_b32_e32 v141, v123
	s_waitcnt vmcnt(2)
	v_lshl_add_u64 v[18:19], s[22:23], 0, v[140:141]
	s_min_i32 s22, s21, 1
	s_lshl_b32 s22, s22, 6
	s_add_i32 s22, s22, s20
	v_mov_b32_e32 v139, v123
	s_ashr_i32 s23, s22, 31
	v_lshl_add_u64 v[16:17], s[26:27], 0, v[138:139]
	s_lshl_b64 s[26:27], s[22:23], 12
	s_add_u32 s26, s24, s26
	s_addc_u32 s27, s25, s27
	s_lshl_b64 s[22:23], s[22:23], 1
	s_add_u32 s22, s0, s22
	s_addc_u32 s23, s1, s23
	v_lshl_add_u64 v[16:17], v[16:17], 0, v[122:123]
	v_lshl_add_u64 v[20:21], v[18:19], 0, v[122:123]
	s_waitcnt vmcnt(0)
	v_lshl_add_u64 v[24:25], s[26:27], 0, v[138:139]
	v_lshl_add_u64 v[26:27], s[22:23], 0, v[140:141]
	v_mov_b32_e32 v16, v240
	v_mov_b32_e32 v17, v241
	v_mov_b32_e32 v18, v242
	v_mov_b32_e32 v19, v243
	s_nop 0
	v_mov_b32_e32 v20, v244
	v_mov_b32_e32 v21, v245
	v_mov_b32_e32 v22, v246
	v_mov_b32_e32 v23, v247
	v_lshl_add_u64 v[24:25], v[24:25], 0, v[122:123]
	v_lshl_add_u64 v[28:29], v[26:27], 0, v[122:123]
	v_mov_b32_e32 v24, v248
	v_mov_b32_e32 v25, v249
	v_mov_b32_e32 v26, v250
	v_mov_b32_e32 v27, v251
	s_nop 0
	v_mov_b32_e32 v28, v252
	v_mov_b32_e32 v29, v253
	v_mov_b32_e32 v30, v254
	v_mov_b32_e32 v31, v255
	s_min_i32 s22, s21, 2
	s_lshl_b32 s22, s22, 6
	s_add_i32 s22, s22, s20
	s_ashr_i32 s23, s22, 31
	s_lshl_b64 s[26:27], s[22:23], 12
	s_add_u32 s26, s24, s26
	s_addc_u32 s27, s25, s27
	s_lshl_b64 s[22:23], s[22:23], 1
	s_add_u32 s22, s0, s22
	s_waitcnt lgkmcnt(3)
	v_lshl_add_u64 v[32:33], s[26:27], 0, v[138:139]
	s_addc_u32 s23, s1, s23
	s_min_i32 s26, s21, 3
	v_lshl_add_u64 v[34:35], s[22:23], 0, v[140:141]
	s_lshl_b32 s22, s26, 6
	s_add_i32 s22, s22, s20
	s_ashr_i32 s23, s22, 31
	s_lshl_b64 s[26:27], s[22:23], 12
	s_add_u32 s24, s24, s26
	s_addc_u32 s25, s25, s27
	s_lshl_b64 s[22:23], s[22:23], 1
	s_add_u32 s22, s0, s22
	v_lshl_add_u64 v[32:33], v[32:33], 0, v[122:123]
	v_lshl_add_u64 v[34:35], v[34:35], 0, v[122:123]
	s_addc_u32 s23, s1, s23
	s_waitcnt lgkmcnt(2)
	global_load_dwordx4 v[36:39], v[32:33], off offset:3072
	s_nop 0
	global_load_dwordx4 v[32:35], v[34:35], off
	s_waitcnt lgkmcnt(1)
	v_lshl_add_u64 v[40:41], s[24:25], 0, v[138:139]
	v_lshl_add_u64 v[42:43], s[22:23], 0, v[140:141]
	v_lshl_add_u64 v[40:41], v[40:41], 0, v[122:123]
	v_lshl_add_u64 v[42:43], v[42:43], 0, v[122:123]
	s_mov_b32 s23, 0
	s_cmp_lt_i32 s21, 1
	s_mov_b32 s24, 0
	s_waitcnt vmcnt(5)
	ds_write_b128 v151, v[16:19]
	s_waitcnt vmcnt(4)
	ds_write2_b64 v187, v[20:21], v[22:23] offset1:2
	s_waitcnt vmcnt(3)
	ds_write_b128 v151, v[24:27] offset:10240
	s_waitcnt vmcnt(2)
	ds_write2_b64 v186, v[28:29], v[30:31] offset1:2
	s_waitcnt lgkmcnt(4)
	global_load_dwordx4 v[44:47], v[40:41], off offset:3072
	s_nop 0
	global_load_dwordx4 v[40:43], v[42:43], off
	s_cselect_b32 s91, 1, 0
	s_add_i32 s98, s90, -1
	s_ashr_i32 s98, s98, 6
	s_cmp_gt_i32 s98, 0
	s_cselect_b32 s99, 0x2000, 0
	s_cselect_b32 s98, 0x80, 0
	s_and_b32 s29, s73, 3
	s_lshl_b32 s29, s29, 1
	s_bfe_u32 s30, s73, 0x10002
	s_or_b32 s29, s29, s30
	s_bfe_u32 s30, s73, 0x1000b
	s_xor_b32 s29, s29, s30
	s_lshl_b32 s29, s29, 16
	s_add_u32 s100, s3, s29
	s_addc_u32 s101, s52, 0
	s_add_u32 s30, s53, s29
	s_addc_u32 s31, s54, 0
	v_mov_b32_e32 v194, v134
	v_mov_b32_e32 v195, 0
	v_mov_b32_e32 v196, v136
	v_mov_b32_e32 v197, 0
	v_lshl_add_u64 v[198:199], s[100:101], 0, v[194:195]
	v_lshl_add_u64 v[200:201], s[30:31], 0, v[196:197]
	v_lshl_add_u64 v[198:199], v[198:199], 0, v[122:123]
	v_lshl_add_u64 v[200:201], v[200:201], 0, v[122:123]
	global_load_dwordx4 v[240:243], v[198:199], off
	global_load_dwordx4 v[244:247], v[200:201], off
	s_add_u32 s100, s100, s99
	s_addc_u32 s101, s101, 0
	s_add_u32 s30, s30, s98
	s_addc_u32 s31, s31, 0
	v_lshl_add_u64 v[198:199], s[100:101], 0, v[194:195]
	v_lshl_add_u64 v[200:201], s[30:31], 0, v[196:197]
	v_lshl_add_u64 v[198:199], v[198:199], 0, v[122:123]
	v_lshl_add_u64 v[200:201], v[200:201], 0, v[122:123]
	global_load_dwordx4 v[248:251], v[198:199], off
	global_load_dwordx4 v[252:255], v[200:201], off
	s_cmp_lg_u32 s91, 0
	s_waitcnt lgkmcnt(0)
	s_barrier
	s_cbranch_scc1 .LBB0_1068
	v_lshl_add_u64 v[16:17], s[0:1], 0, v[140:141]
	v_lshl_add_u64 v[106:107], v[16:17], 0, v[122:123]
	v_add_u32_e32 v16, s74, v171
	v_mov_b32_e32 v86, 0
	s_add_i32 s22, s74, 0xfffffe10
	v_subrev_u32_e32 v81, s20, v16
	v_mov_b32_e32 v87, v86
	v_mov_b32_e32 v88, v86
	v_mov_b32_e32 v89, v86
	s_mov_b32 s23, 5
	v_mov_b32_e32 v90, v86
	v_mov_b32_e32 v91, v86
	v_mov_b32_e32 v92, v86
	v_mov_b32_e32 v93, v86
	v_mov_b32_e32 v94, v86
	v_mov_b32_e32 v95, v86
	v_mov_b32_e32 v96, v86
	v_mov_b32_e32 v97, v86
	v_mov_b32_e32 v98, v86
	v_mov_b32_e32 v99, v86
	v_mov_b32_e32 v100, v86
	v_mov_b32_e32 v101, v86
	v_mov_b32_e32 v102, v86
	v_mov_b32_e32 v103, v86
	v_mov_b32_e32 v104, v86
	v_mov_b32_e32 v105, v86
